# scan: static s_setprio 1 for the consumer waves 4-7 during the HGRN scan (reset to 0 after)
# speedup vs baseline: 1.0135x; 1.0047x over previous
.LBB0_384:
	s_or_b64 exec, exec, s[68:69]
	s_lshr_b32 s75, s74, 6
	s_cmpk_gt_u32 s74, 0xff
	s_mov_b64 s[0:1], -1
	s_cbranch_scc0 .LBB0_396
	s_setprio 1
	s_and_b32 s0, s94, 15
	s_lshl_b32 s72, s0, 22
	s_add_i32 s73, s75, -4
	s_cmp_lg_u32 s73, 0
	s_cselect_b64 s[0:1], -1, 0
	s_cmpk_lt_u32 s74, 0x1c0
	s_cselect_b64 s[68:69], -1, 0
	s_not_b32 s70, s75
	s_lshl_b32 s70, s70, 5
	s_and_b32 s87, s70, 32
	s_add_i32 s70, s75, -5
	v_or_b32_e32 v2, s87, v83
	s_cmp_lt_u32 s70, 2
	v_mul_u32_u24_e32 v3, 0x110, v2
	s_cselect_b64 s[70:71], -1, 0
	v_mul_u32_u24_e32 v105, 0x50, v2
	v_lshl_add_u32 v106, s73, 7, v90
	v_lshl_or_b32 v2, s73, 5, v83
	v_lshl_add_u32 v108, s73, 6, v91
	s_add_i32 s73, s87, s95
	s_waitcnt lgkmcnt(0)
	s_barrier
	s_add_i32 s73, s73, s86
	s_waitcnt lgkmcnt(0)
	s_barrier
	s_movk_i32 s88, 0x50
	s_lshl_b32 s73, s73, 1
	v_mul_lo_u32 v107, v2, s88
	s_or_b32 s72, s72, s73
	s_mov_b32 s73, s96
	v_mov_b32_e32 v2, 0
	s_mov_b32 s87, 1
	v_lshl_add_u64 v[80:81], v[78:79], 0, s[72:73]
	v_add_u32_e32 v109, v86, v3
	v_mov_b32_e32 v3, v2
	v_mov_b32_e32 v4, v2
	v_mov_b32_e32 v5, v2
	s_waitcnt vmcnt(0)
	v_mov_b32_e32 v6, v2
	v_mov_b32_e32 v7, v2
	v_mov_b32_e32 v8, v2
	v_mov_b32_e32 v9, v2
	v_mov_b32_e32 v10, v2
	v_mov_b32_e32 v11, v2
	v_mov_b32_e32 v12, v2
	v_mov_b32_e32 v13, v2
	v_mov_b32_e32 v14, v2
	v_mov_b32_e32 v15, v2
	v_mov_b32_e32 v16, v2
	v_mov_b32_e32 v17, v2
	v_mov_b32_e32 v18, v2
	v_mov_b32_e32 v19, v2
	v_mov_b32_e32 v20, v2
	v_mov_b32_e32 v21, v2
	v_mov_b32_e32 v22, v2
	v_mov_b32_e32 v23, v2
	v_mov_b32_e32 v24, v2
	v_mov_b32_e32 v25, v2
	v_mov_b32_e32 v26, v2
	v_mov_b32_e32 v27, v2
	v_mov_b32_e32 v28, v2
	v_mov_b32_e32 v29, v2
	v_mov_b32_e32 v30, v2
	v_mov_b32_e32 v31, v2
	v_mov_b32_e32 v32, v2
	v_mov_b32_e32 v33, v2
	s_branch .LBB0_387

.LBB0_415:
	s_or_b64 exec, exec, s[68:69]
	v_readfirstlane_b32 s88, v0
	s_lshl_b32 s0, s94, 12
	s_lshr_b32 s87, s88, 6
	s_cmpk_gt_u32 s88, 0xff
	s_mov_b64 s[68:69], -1
	s_cbranch_scc0 .LBB0_427
	s_setprio 1
	s_mov_b32 s1, s96
	s_lshl_b64 s[74:75], s[0:1], 10
	s_add_i32 s92, s87, -4
	s_cmp_lg_u32 s92, 0
	s_cselect_b64 s[68:69], -1, 0
	s_cmpk_lt_u32 s88, 0x1c0
	s_cselect_b64 s[70:71], -1, 0
	s_not_b32 s72, s87
	s_lshl_b32 s72, s72, 5
	s_and_b32 s93, s72, 32
	s_add_i32 s72, s87, -5
	v_or_b32_e32 v2, s93, v83
	s_cmp_lt_u32 s72, 2
	v_mul_u32_u24_e32 v3, 0x110, v2
	s_cselect_b64 s[72:73], -1, 0
	v_mul_u32_u24_e32 v105, 0x50, v2
	v_lshl_add_u32 v106, s92, 7, v90
	v_lshl_or_b32 v2, s92, 5, v83
	v_lshl_add_u32 v108, s92, 6, v91
	s_add_i32 s92, s93, s95
	s_add_i32 s92, s92, s86
	s_waitcnt lgkmcnt(0)
	s_barrier
	s_lshl_b32 s86, s92, 1
	s_waitcnt lgkmcnt(0)
	s_barrier
	s_movk_i32 vcc_lo, 0x50
	s_add_u32 s74, s74, s86
	v_mul_lo_u32 v107, v2, vcc_lo
	s_addc_u32 s75, s75, 0
	v_mov_b32_e32 v2, 0
	s_mov_b32 s1, 0
	v_lshl_add_u64 v[80:81], v[76:77], 0, s[74:75]
	s_mov_b64 s[74:75], 0
	v_add_u32_e32 v109, v86, v3
	v_mov_b32_e32 v3, v2
	v_mov_b32_e32 v4, v2
	v_mov_b32_e32 v5, v2
	s_waitcnt vmcnt(0)
	v_mov_b32_e32 v6, v2
	v_mov_b32_e32 v7, v2
	v_mov_b32_e32 v8, v2
	v_mov_b32_e32 v9, v2
	v_mov_b32_e32 v10, v2
	v_mov_b32_e32 v11, v2
	v_mov_b32_e32 v12, v2
	v_mov_b32_e32 v13, v2
	v_mov_b32_e32 v14, v2
	v_mov_b32_e32 v15, v2
	v_mov_b32_e32 v16, v2
	v_mov_b32_e32 v17, v2
	v_mov_b32_e32 v18, v2
	v_mov_b32_e32 v19, v2
	v_mov_b32_e32 v20, v2
	v_mov_b32_e32 v21, v2
	v_mov_b32_e32 v22, v2
	v_mov_b32_e32 v23, v2
	v_mov_b32_e32 v24, v2
	v_mov_b32_e32 v25, v2
	v_mov_b32_e32 v26, v2
	v_mov_b32_e32 v27, v2
	v_mov_b32_e32 v28, v2
	v_mov_b32_e32 v29, v2
	v_mov_b32_e32 v30, v2
	v_mov_b32_e32 v31, v2
	v_mov_b32_e32 v32, v2
	v_mov_b32_e32 v33, v2
	s_branch .LBB0_418

.LBB0_438:
	s_setprio 0
	v_readlane_b32 s86, v255, 17
	v_readlane_b32 s87, v255, 18
	v_readlane_b32 s84, v255, 21
	v_readlane_b32 s88, v255, 23
	v_readlane_b32 s90, v255, 25
	v_readlane_b32 s92, v255, 27
	v_readlane_b32 s94, v255, 29
	v_mov_b32_e32 v83, v73
	v_readlane_b32 s85, v255, 22
	v_readlane_b32 s89, v255, 24
	v_readlane_b32 s91, v255, 26
	v_readlane_b32 s93, v255, 28
	v_readlane_b32 s87, v255, 36
	v_readlane_b32 s95, v255, 30
